# GDN scan spread over 32 workgroups (one b,h each) + re-pipelined scan MFMA path + P1/P8 wide-store epilogues
# speedup vs baseline: 1.0388x; 1.0388x over previous
.LBB0_3200:
	s_or_b64 exec, exec, s[0:1]
	v_readfirstlane_b32 s14, v208
	s_bfe_u32 s33, s14, 0x10008
	s_cmp_lt_u32 s50, 32
	v_lshrrev_b32_e32 v2, 1, v208
	v_bfe_u32 v170, v208, 3, 5
	v_lshlrev_b32_e32 v3, 3, v208
	s_waitcnt lgkmcnt(0)
	s_barrier
	s_cbranch_scc1 .LBB0_3202
.Lattn_setup:
	s_waitcnt vmcnt(0)
	v_and_b32_e32 v157, 0xff, v208
	v_and_b32_e32 v185, 0x60, v2
	v_and_b32_e32 v0, 31, v208
	v_or_b32_e32 v171, 0x100, v157
	v_or_b32_e32 v186, v185, v0
	v_or_b32_e32 v172, 0x200, v157
	v_bfe_u32 v1, v208, 3, 5
	v_and_b32_e32 v156, 56, v3
	v_lshrrev_b32_e32 v173, 3, v171
	v_mul_u32_u24_e32 v187, 0x44, v0
	s_mul_i32 s36, s33, 0x12200
	s_cbranch_execz .LBB0_3203
	s_branch .LBB0_3216

.LBB0_3203:
	s_cmp_eq_u32 s33, 1
	s_cbranch_scc1 .Lscan_passive
	s_mov_b32 s5, s50
	s_waitcnt vmcnt(0)
	v_and_b32_e32 v157, 0xff, v208
	s_lshr_b32 s12, s50, 3
	s_mul_i32 s4, s5, 0x28a000
	s_add_u32 s0, s60, s4
	v_or_b32_e32 v171, 0x100, v157
	s_addc_u32 s1, s61, 0
	v_lshlrev_b32_e32 v0, 4, v157
	v_lshlrev_b32_e32 v1, 4, v171
	v_or_b32_e32 v172, 0x200, v157
	v_or_b32_e32 v8, 0x300, v208
	s_barrier
	global_load_dwordx4 v[96:99], v0, s[0:1]
	global_load_dwordx4 v[100:103], v1, s[0:1]
	v_lshlrev_b32_e32 v1, 4, v172
	v_lshlrev_b32_e32 v4, 4, v8
	v_or_b32_e32 v9, 0x400, v157
	v_or_b32_e32 v10, 0x500, v157
	global_load_dwordx4 v[104:107], v4, s[0:1]
	v_lshlrev_b32_e32 v5, 4, v9
	global_load_dwordx4 v[108:111], v1, s[0:1]
	global_load_dwordx4 v[112:115], v5, s[0:1]
	v_lshlrev_b32_e32 v1, 4, v10
	v_or_b32_e32 v11, 0x600, v157
	v_or_b32_e32 v12, 0x700, v208
	v_or_b32_e32 v13, 0x800, v157
	v_lshlrev_b32_e32 v5, 4, v11
	global_load_dwordx4 v[116:119], v1, s[0:1]
	global_load_dwordx4 v[120:123], v5, s[0:1]
	v_lshlrev_b32_e32 v6, 4, v12
	v_lshlrev_b32_e32 v1, 4, v13
	v_or_b32_e32 v14, 0x900, v157
	global_load_dwordx4 v[124:127], v6, s[0:1]
	global_load_dwordx4 v[128:131], v1, s[0:1]
	v_lshlrev_b32_e32 v1, 4, v14
	global_load_dwordx4 v[132:135], v1, s[0:1]
	v_and_b32_e32 v156, 56, v3
	v_lshrrev_b32_e32 v8, 3, v8
	v_lshlrev_b32_e32 v3, 1, v156
	v_mul_u32_u24_e32 v8, 0x88, v8
	v_lshrrev_b32_e32 v9, 3, v9
	v_mul_u32_u24_e32 v15, 0x88, v170
	v_add3_u32 v175, s36, v8, v3
	v_mul_u32_u24_e32 v8, 0x88, v9
	v_lshrrev_b32_e32 v12, 3, v12
	v_add3_u32 v174, s36, v15, v3
	v_lshrrev_b32_e32 v173, 3, v171
	v_lshrrev_b32_e32 v15, 3, v172
	v_lshrrev_b32_e32 v10, 3, v10
	v_lshrrev_b32_e32 v11, 3, v11
	v_lshrrev_b32_e32 v13, 3, v13
	v_add3_u32 v179, s36, v8, v3
	v_lshrrev_b32_e32 v8, 3, v14
	s_mov_b32 s1, 0
	s_mul_i32 s0, s5, 0x41
	v_mul_u32_u24_e32 v12, 0x88, v12
	v_mul_u32_u24_e32 v16, 0x88, v173
	v_mul_u32_u24_e32 v15, 0x88, v15
	v_mul_u32_u24_e32 v9, 0x88, v10
	v_mul_u32_u24_e32 v10, 0x88, v11
	v_mul_u32_u24_e32 v11, 0x88, v13
	v_mul_u32_u24_e32 v8, 0x88, v8
	v_add3_u32 v176, s36, v12, v3
	s_lshl_b64 s[0:1], s[0:1], 2
	v_add3_u32 v177, s36, v16, v3
	v_add3_u32 v178, s36, v15, v3
	v_add3_u32 v180, s36, v9, v3
	v_add3_u32 v181, s36, v10, v3
	v_add3_u32 v182, s36, v11, v3
	v_add3_u32 v183, s36, v8, v3
	v_mbcnt_hi_u32_b32 v3, -1, v209
	s_add_u32 s0, s90, s0
	v_and_b32_e32 v9, 64, v3
	s_addc_u32 s1, s91, s1
	v_xor_b32_e32 v8, 1, v3
	v_add_u32_e32 v9, 64, v9
	s_add_u32 s0, s0, 0x13d6000
	v_cmp_lt_i32_e32 vcc, v8, v9
	s_addc_u32 s1, s1, 0
	s_lshl_b32 s5, s5, 7
	v_cndmask_b32_e32 v8, v3, v8, vcc
	v_lshlrev_b32_e32 v188, 2, v8
	v_xor_b32_e32 v8, 2, v3
	s_and_b32 s5, s5, 0x380
	v_mov_b32_e32 v1, 0
	v_and_b32_e32 v11, 48, v213
	v_cmp_lt_i32_e32 vcc, v8, v9
	s_add_u32 s6, s58, s5
	s_addc_u32 s7, s59, 0
	v_cndmask_b32_e32 v3, v3, v8, vcc
	v_lshlrev_b32_e32 v8, 1, v11
	v_mov_b32_e32 v9, v1
	v_lshl_add_u64 v[158:159], s[6:7], 0, v[8:9]
	s_add_u32 s6, s90, s5
	s_addc_u32 s7, s91, 0
	v_bfe_u32 v10, v208, 2, 6
	v_lshlrev_b32_e32 v189, 2, v3
	v_and_b32_e32 v185, 0x60, v2
	v_lshl_add_u64 v[2:3], s[6:7], 0, v[8:9]
	s_mov_b64 s[6:7], 0x241ba00
	v_or_b32_e32 v186, v185, v211
	v_and_b32_e32 v12, 4, v212
	v_lshl_add_u64 v[160:161], v[2:3], 0, s[6:7]
	v_mul_u32_u24_e32 v3, 0x104, v10
	v_lshlrev_b32_e32 v2, 2, v11
	v_readlane_b32 s16, v239, 4
	s_add_u32 s4, s90, s4
	s_movk_i32 s8, 0x88
	v_mov_b32_e32 v5, v1
	v_mov_b32_e32 v7, v1
	v_lshl_add_u32 v13, v12, 1, s36
	v_mul_u32_u24_e32 v187, 0x44, v211
	v_lshl_add_u32 v16, v186, 2, s36
	v_mul_u32_u24_e32 v17, 0x104, v12
	v_add3_u32 v192, s36, v3, v2
	v_mov_b32_e32 v3, v1
	v_readlane_b32 s17, v239, 5
	s_addc_u32 s5, s91, 0
	v_mov_b32_e32 v14, v1
	v_mov_b32_e32 v15, v1
	v_subrev_u32_e32 v184, 48, v10
	s_movk_i32 s2, 0x80
	v_mad_u32_u24 v190, v186, s8, v13
	v_lshl_add_u32 v191, v187, 1, v13
	v_readlane_b32 s18, v239, 6
	v_lshl_add_u64 v[162:163], s[16:17], 0, v[2:3]
	v_lshl_add_u64 v[164:165], s[4:5], 0, v[0:1]
	v_lshl_add_u64 v[166:167], s[4:5], 0, v[4:5]
	v_lshl_add_u64 v[168:169], s[4:5], 0, v[6:7]
	v_mov_b32_e32 v0, v1
	v_mov_b32_e32 v2, v1
	v_mov_b32_e32 v4, v1
	v_mov_b32_e32 v6, v1
	v_mov_b32_e32 v8, v1
	v_mov_b32_e32 v10, v1
	v_mov_b32_e32 v11, v1
	v_mov_b32_e32 v12, v1
	v_mov_b32_e32 v13, v1
	v_add_u32_e32 v193, v16, v17
	v_mov_b64_e32 v[30:31], v[14:15]
	v_mov_b64_e32 v[46:47], v[14:15]
	v_cmp_gt_u32_e64 s[2:3], s2, v157
	s_mulk_i32 s12, 0x1010
	s_mov_b64 s[6:7], 0
	s_mov_b32 s13, 0x6d45000
	s_mov_b32 s15, 0x6d49000
	s_mov_b32 s16, 0x6d4a000
	s_mov_b32 s17, 0x6d4b000
	v_mov_b32_e32 v194, 0x358637bd
	s_mov_b32 s18, 0x800000
	v_mov_b64_e32 v[28:29], v[12:13]
	v_mov_b64_e32 v[26:27], v[10:11]
	v_mov_b64_e32 v[24:25], v[8:9]
	v_mov_b64_e32 v[22:23], v[6:7]
	v_mov_b64_e32 v[20:21], v[4:5]
	v_mov_b64_e32 v[18:19], v[2:3]
	v_mov_b64_e32 v[16:17], v[0:1]
	v_mov_b64_e32 v[44:45], v[12:13]
	v_mov_b64_e32 v[42:43], v[10:11]
	v_mov_b64_e32 v[40:41], v[8:9]
	v_mov_b64_e32 v[38:39], v[6:7]
	v_mov_b64_e32 v[36:37], v[4:5]
	v_mov_b64_e32 v[34:35], v[2:3]
	v_mov_b64_e32 v[32:33], v[0:1]
	global_load_dwordx4 v[240:243], v[162:163], off
	global_load_dwordx4 v[244:247], v[162:163], off offset:16
	global_load_dwordx4 v[248:251], v[162:163], off offset:48
	global_load_dwordx4 v[252:255], v[162:163], off offset:32
	global_load_dword v236, v1, s[0:1]
	s_waitcnt vmcnt(9)
	ds_write2_b64 v174, v[96:97], v[98:99] offset1:1
	s_waitcnt vmcnt(8)
	ds_write2_b64 v177, v[100:101], v[102:103] offset1:1
	s_waitcnt vmcnt(6)
	ds_write2_b64 v178, v[108:109], v[110:111] offset1:1
	ds_write2_b64 v175, v[104:105], v[106:107] offset1:1
	s_waitcnt vmcnt(5)
	ds_write2_b64 v179, v[112:113], v[114:115] offset1:1
	s_waitcnt vmcnt(4)
	ds_write2_b64 v180, v[116:117], v[118:119] offset1:1
	s_waitcnt vmcnt(3)
	ds_write2_b64 v181, v[120:121], v[122:123] offset1:1
	s_waitcnt vmcnt(2)
	ds_write2_b64 v176, v[124:125], v[126:127] offset1:1
	s_waitcnt vmcnt(1)
	ds_write2_b64 v182, v[128:129], v[130:131] offset1:1
	s_waitcnt vmcnt(0)
	ds_write2_b64 v183, v[132:133], v[134:135] offset1:1
	s_waitcnt lgkmcnt(0)
	s_barrier
	v_readlane_b32 s19, v239, 7
	v_readlane_b32 s20, v239, 8
	v_readlane_b32 s21, v239, 9
	v_readlane_b32 s22, v239, 10
	v_readlane_b32 s23, v239, 11
	v_readlane_b32 s24, v239, 12
	v_readlane_b32 s25, v239, 13
	v_readlane_b32 s26, v239, 14
	v_readlane_b32 s27, v239, 15
	v_readlane_b32 s28, v239, 16
	v_readlane_b32 s29, v239, 17
	v_readlane_b32 s30, v239, 18
	v_readlane_b32 s31, v239, 19
	s_branch .LBB0_3205
.LBB0_3204:
	v_mov_b32_e32 v236, v237
	s_add_u32 s6, s6, 0xa000
	s_addc_u32 s7, s7, 0
	s_add_u32 s0, s0, 4
	s_addc_u32 s1, s1, 0
	s_cmp_lg_u32 s6, 0x28a000
	v_add_u32_e32 v184, 64, v184
	s_waitcnt lgkmcnt(0)
	s_barrier
	s_cbranch_scc0 .LBB0_3215
.LBB0_3205:
	global_load_dword v237, v1, s[0:1] offset:4
	v_cmp_lt_i32_e64 s[4:5], -1, v184
	v_add_u32_e32 v0, s12, v184
	v_mov_b32_e32 v2, 0
	v_mov_b32_e32 v3, 0
	v_mov_b32_e32 v4, 0
	v_mov_b32_e32 v5, 0
	v_mov_b32_e32 v6, 0
	v_mov_b32_e32 v7, 0
	v_mov_b32_e32 v8, 0
	v_mov_b32_e32 v9, 0
	s_and_saveexec_b64 s[8:9], s[4:5]
	s_cbranch_execz .LBB0_3207
	v_lshlrev_b64 v[2:3], 10, v[0:1]
	v_lshl_add_u64 v[6:7], v[158:159], 0, v[2:3]
	global_load_dwordx4 v[2:5], v[6:7], off offset:16
	s_nop 0
	global_load_dwordx4 v[6:9], v[6:7], off

.LBB0_3209:
	s_and_saveexec_b64 s[10:11], s[2:3]
	s_cbranch_execz .LBB0_3211
	ds_read2_b64 v[48:51], v190 offset1:2
	ds_read2_b64 v[52:55], v190 offset0:4 offset1:6
	ds_read2_b64 v[56:59], v190 offset0:8 offset1:10
	ds_read2_b64 v[60:63], v190 offset0:12 offset1:14
	v_add_u32_e32 v14, 0x2200, v191
	ds_read2_b64 v[214:217], v14 offset1:2
	v_add_u32_e32 v15, 0x3300, v191
	ds_read2_b64 v[218:221], v15 offset1:2
	ds_read2_b64 v[222:225], v14 offset0:4 offset1:6
	ds_read2_b64 v[226:229], v15 offset0:4 offset1:6
	ds_read2_b64 v[230:233], v14 offset0:8 offset1:10
	v_cvt_pk_bf16_f32 v136, v16, v17
	v_cvt_pk_bf16_f32 v137, v18, v19
	v_cvt_pk_bf16_f32 v138, v20, v21
	v_cvt_pk_bf16_f32 v139, v22, v23
	v_cvt_pk_bf16_f32 v152, v24, v25
	v_cvt_pk_bf16_f32 v153, v26, v27
	v_cvt_pk_bf16_f32 v154, v28, v29
	v_cvt_pk_bf16_f32 v155, v30, v31
	v_cvt_pk_bf16_f32 v140, v32, v33
	v_cvt_pk_bf16_f32 v141, v34, v35
	v_cvt_pk_bf16_f32 v142, v36, v37
	v_cvt_pk_bf16_f32 v143, v38, v39
	v_cvt_pk_bf16_f32 v148, v40, v41
	v_cvt_pk_bf16_f32 v149, v42, v43
	v_cvt_pk_bf16_f32 v150, v44, v45
	v_cvt_pk_bf16_f32 v151, v46, v47
	s_waitcnt lgkmcnt(8)
	v_lshlrev_b32_e32 v64, 16, v48
	v_and_b32_e32 v65, 0xffff0000, v48
	v_lshlrev_b32_e32 v66, 16, v49
	v_and_b32_e32 v67, 0xffff0000, v49
	v_lshlrev_b32_e32 v68, 16, v50
	v_and_b32_e32 v69, 0xffff0000, v50
	v_lshlrev_b32_e32 v70, 16, v51
	v_and_b32_e32 v71, 0xffff0000, v51
	s_waitcnt lgkmcnt(7)
	v_lshlrev_b32_e32 v72, 16, v52
	v_and_b32_e32 v73, 0xffff0000, v52
	v_lshlrev_b32_e32 v74, 16, v53
	v_and_b32_e32 v75, 0xffff0000, v53
	v_lshlrev_b32_e32 v76, 16, v54
	v_and_b32_e32 v77, 0xffff0000, v54
	v_lshlrev_b32_e32 v78, 16, v55
	v_and_b32_e32 v79, 0xffff0000, v55
	s_waitcnt lgkmcnt(6)
	v_lshlrev_b32_e32 v80, 16, v56
	v_and_b32_e32 v81, 0xffff0000, v56
	v_lshlrev_b32_e32 v82, 16, v57
	v_and_b32_e32 v83, 0xffff0000, v57
	v_lshlrev_b32_e32 v84, 16, v58
	v_and_b32_e32 v85, 0xffff0000, v58
	v_lshlrev_b32_e32 v86, 16, v59
	v_and_b32_e32 v87, 0xffff0000, v59
	s_waitcnt lgkmcnt(5)
	v_lshlrev_b32_e32 v88, 16, v60
	v_and_b32_e32 v89, 0xffff0000, v60
	v_lshlrev_b32_e32 v90, 16, v61
	v_and_b32_e32 v91, 0xffff0000, v61
	v_lshlrev_b32_e32 v92, 16, v62
	v_and_b32_e32 v93, 0xffff0000, v62
	v_lshlrev_b32_e32 v94, 16, v63
	v_and_b32_e32 v95, 0xffff0000, v63
	s_nop 1
	s_waitcnt lgkmcnt(4)
	v_mfma_f32_32x32x16_bf16 v[64:79], v[214:217], v[136:139], v[64:79]
	ds_read2_b64 v[10:13], v15 offset0:8 offset1:10
	s_waitcnt lgkmcnt(4)
	v_mfma_f32_32x32x16_bf16 v[80:95], v[218:221], v[136:139], v[80:95]
	ds_read2_b64 v[214:217], v14 offset0:12 offset1:14
	s_waitcnt lgkmcnt(4)
	v_mfma_f32_32x32x16_bf16 v[64:79], v[222:225], v[152:155], v[64:79]
	ds_read2_b64 v[218:221], v15 offset0:12 offset1:14
	s_waitcnt lgkmcnt(4)
	v_mfma_f32_32x32x16_bf16 v[80:95], v[226:229], v[152:155], v[80:95]
	v_add_u32_e32 v234, 0x4400, v191
	ds_read2_b64 v[222:225], v234 offset1:2
	s_waitcnt lgkmcnt(4)
	v_mfma_f32_32x32x16_bf16 v[64:79], v[230:233], v[140:143], v[64:79]
	v_add_u32_e32 v235, 0x5500, v191
	ds_read2_b64 v[226:229], v235 offset1:2
	s_waitcnt lgkmcnt(4)
	v_mfma_f32_32x32x16_bf16 v[80:95], v[10:13], v[140:143], v[80:95]
	v_add_u32_e32 v238, 0x6600, v191
	ds_read2_b64 v[230:233], v238 offset1:2
	s_waitcnt lgkmcnt(4)
	v_mfma_f32_32x32x16_bf16 v[64:79], v[214:217], v[148:151], v[64:79]
	v_add_u32_e32 v14, 0x7700, v191
	ds_read2_b64 v[10:13], v14 offset1:2
	s_waitcnt lgkmcnt(4)
	v_mfma_f32_32x32x16_bf16 v[80:95], v[218:221], v[148:151], v[80:95]
	ds_read2_b64 v[214:217], v234 offset0:4 offset1:6
	s_waitcnt lgkmcnt(4)
	v_mfma_f32_32x32x16_bf16 v[48:63], v[222:225], v[136:139], 0
	ds_read2_b64 v[218:221], v235 offset0:4 offset1:6
	s_nop 7
	s_nop 1
	v_cvt_pk_bf16_f32 v144, v64, v65
	v_cvt_pk_bf16_f32 v145, v66, v67
	v_cvt_pk_bf16_f32 v146, v68, v69
	v_cvt_pk_bf16_f32 v147, v70, v71
	v_cvt_pk_bf16_f32 v196, v72, v73
	v_cvt_pk_bf16_f32 v197, v74, v75
	v_cvt_pk_bf16_f32 v198, v76, v77
	v_cvt_pk_bf16_f32 v199, v78, v79
	v_cvt_pk_bf16_f32 v200, v80, v81
	v_cvt_pk_bf16_f32 v201, v82, v83
	v_cvt_pk_bf16_f32 v202, v84, v85
	v_cvt_pk_bf16_f32 v203, v86, v87
	v_cvt_pk_bf16_f32 v204, v88, v89
	v_cvt_pk_bf16_f32 v205, v90, v91
	v_cvt_pk_bf16_f32 v206, v92, v93
	v_cvt_pk_bf16_f32 v207, v94, v95
	s_nop 0
	s_waitcnt lgkmcnt(4)
	v_mfma_f32_32x32x16_bf16 v[64:79], v[226:229], v[136:139], 0
	ds_read2_b64 v[222:225], v238 offset0:4 offset1:6
	s_waitcnt lgkmcnt(4)
	v_mfma_f32_32x32x16_bf16 v[48:63], v[230:233], v[144:147], v[48:63]
	ds_read2_b64 v[226:229], v14 offset0:4 offset1:6
	s_waitcnt lgkmcnt(4)
	v_mfma_f32_32x32x16_bf16 v[64:79], v[10:13], v[144:147], v[64:79]
	ds_read2_b64 v[230:233], v234 offset0:8 offset1:10
	s_waitcnt lgkmcnt(4)
	v_mfma_f32_32x32x16_bf16 v[48:63], v[214:217], v[152:155], v[48:63]
	ds_read2_b64 v[10:13], v235 offset0:8 offset1:10
	s_waitcnt lgkmcnt(4)
	v_mfma_f32_32x32x16_bf16 v[64:79], v[218:221], v[152:155], v[64:79]
	ds_read2_b64 v[214:217], v238 offset0:8 offset1:10
	s_waitcnt lgkmcnt(4)
	v_mfma_f32_32x32x16_bf16 v[48:63], v[222:225], v[196:199], v[48:63]
	ds_read2_b64 v[218:221], v14 offset0:8 offset1:10
	s_waitcnt lgkmcnt(4)
	v_mfma_f32_32x32x16_bf16 v[64:79], v[226:229], v[196:199], v[64:79]
	ds_read2_b64 v[222:225], v234 offset0:12 offset1:14
	v_mul_f32_e64 v30, v30, v236
	v_mul_f32_e64 v31, v31, v236
	v_pk_mul_f32 v[28:29], v[28:29], v[236:237] op_sel_hi:[1,0]
	v_pk_mul_f32 v[26:27], v[26:27], v[236:237] op_sel_hi:[1,0]
	v_pk_mul_f32 v[24:25], v[24:25], v[236:237] op_sel_hi:[1,0]
	v_pk_mul_f32 v[22:23], v[22:23], v[236:237] op_sel_hi:[1,0]
	v_mul_f32_e64 v20, v20, v236
	v_mul_f32_e64 v21, v21, v236
	v_mul_f32_e64 v18, v18, v236
	v_mul_f32_e64 v19, v19, v236
	v_pk_mul_f32 v[16:17], v[16:17], v[236:237] op_sel_hi:[1,0]
	v_pk_mul_f32 v[46:47], v[46:47], v[236:237] op_sel_hi:[1,0]
	v_pk_mul_f32 v[44:45], v[44:45], v[236:237] op_sel_hi:[1,0]
	v_pk_mul_f32 v[42:43], v[42:43], v[236:237] op_sel_hi:[1,0]
	v_mul_f32_e64 v40, v40, v236
	v_mul_f32_e64 v41, v41, v236
	v_mul_f32_e64 v38, v38, v236
	v_mul_f32_e64 v39, v39, v236
	v_pk_mul_f32 v[36:37], v[36:37], v[236:237] op_sel_hi:[1,0]
	v_pk_mul_f32 v[34:35], v[34:35], v[236:237] op_sel_hi:[1,0]
	v_pk_mul_f32 v[32:33], v[32:33], v[236:237] op_sel_hi:[1,0]
	s_waitcnt lgkmcnt(4)
	v_mfma_f32_32x32x16_bf16 v[48:63], v[230:233], v[140:143], v[48:63]
	ds_read2_b64 v[226:229], v235 offset0:12 offset1:14
	s_waitcnt lgkmcnt(4)
	v_mfma_f32_32x32x16_bf16 v[64:79], v[10:13], v[140:143], v[64:79]
	ds_read2_b64 v[230:233], v238 offset0:12 offset1:14
	s_waitcnt lgkmcnt(4)
	v_mfma_f32_32x32x16_bf16 v[48:63], v[214:217], v[200:203], v[48:63]
	ds_read2_b64 v[10:13], v14 offset0:12 offset1:14
	s_waitcnt lgkmcnt(4)
	v_mfma_f32_32x32x16_bf16 v[64:79], v[218:221], v[200:203], v[64:79]
	v_add_u32_e32 v15, 0x8800, v191
	ds_read2_b64 v[214:217], v15 offset1:2
	s_waitcnt lgkmcnt(4)
	v_mfma_f32_32x32x16_bf16 v[48:63], v[222:225], v[148:151], v[48:63]
	v_add_u32_e32 v234, 0x9900, v191
	ds_read2_b64 v[218:221], v234 offset1:2
	s_waitcnt lgkmcnt(4)
	v_mfma_f32_32x32x16_bf16 v[64:79], v[226:229], v[148:151], v[64:79]
	ds_read2_b64 v[222:225], v15 offset0:4 offset1:6
	s_waitcnt lgkmcnt(4)
	v_mfma_f32_32x32x16_bf16 v[48:63], v[230:233], v[204:207], v[48:63]
	ds_read2_b64 v[226:229], v234 offset0:4 offset1:6
	s_waitcnt lgkmcnt(4)
	v_mfma_f32_32x32x16_bf16 v[64:79], v[10:13], v[204:207], v[64:79]
	ds_read2_b64 v[230:233], v15 offset0:8 offset1:10
	s_waitcnt lgkmcnt(4)
	v_mfma_f32_32x32x16_bf16 v[16:31], v[214:217], v[144:147], v[16:31]
	ds_read2_b64 v[10:13], v234 offset0:8 offset1:10
	s_waitcnt lgkmcnt(4)
	v_mfma_f32_32x32x16_bf16 v[32:47], v[218:221], v[144:147], v[32:47]
	ds_read2_b64 v[214:217], v15 offset0:12 offset1:14
	s_waitcnt lgkmcnt(4)
	v_mfma_f32_32x32x16_bf16 v[16:31], v[222:225], v[196:199], v[16:31]
	ds_read2_b64 v[218:221], v234 offset0:12 offset1:14
	s_waitcnt lgkmcnt(4)
	v_mfma_f32_32x32x16_bf16 v[32:47], v[226:229], v[196:199], v[32:47]
	s_waitcnt lgkmcnt(3)
	v_mfma_f32_32x32x16_bf16 v[16:31], v[230:233], v[200:203], v[16:31]
	s_waitcnt lgkmcnt(2)
	v_mfma_f32_32x32x16_bf16 v[32:47], v[10:13], v[200:203], v[32:47]
	v_add_u32_e32 v15, 0xa800, v193
	ds_write2_b32 v15, v48, v49 offset0:128 offset1:193
	v_add_u32_e32 v15, 0xac00, v193
	ds_write2_b32 v15, v50, v51 offset0:2 offset1:67
	v_add_u32_e32 v15, 0xb000, v193
	ds_write2_b32 v15, v52, v53 offset0:136 offset1:201
	v_add_u32_e32 v15, 0xb400, v193
	ds_write2_b32 v15, v54, v55 offset0:10 offset1:75
	v_add_u32_e32 v15, 0xb800, v193
	ds_write2_b32 v15, v56, v57 offset0:144 offset1:209
	v_add_u32_e32 v15, 0xbc00, v193
	ds_write2_b32 v15, v58, v59 offset0:18 offset1:83
	v_add_u32_e32 v15, 0xc000, v193
	ds_write2_b32 v15, v60, v61 offset0:152 offset1:217
	v_add_u32_e32 v15, 0xc400, v193
	ds_write2_b32 v15, v62, v63 offset0:26 offset1:91
	s_waitcnt lgkmcnt(9)
	v_mfma_f32_32x32x16_bf16 v[16:31], v[214:217], v[204:207], v[16:31]
	s_waitcnt lgkmcnt(8)
	v_mfma_f32_32x32x16_bf16 v[32:47], v[218:221], v[204:207], v[32:47]
	v_add_u32_e32 v15, 0xc800, v193
	ds_write2_b32 v15, v64, v65 offset0:160 offset1:225
	v_add_u32_e32 v15, 0xcc00, v193
	ds_write2_b32 v15, v66, v67 offset0:34 offset1:99
	v_add_u32_e32 v15, 0xd000, v193
	ds_write2_b32 v15, v68, v69 offset0:168 offset1:233
	v_add_u32_e32 v15, 0xd400, v193
	ds_write2_b32 v15, v70, v71 offset0:42 offset1:107
	v_add_u32_e32 v15, 0xd800, v193
	ds_write2_b32 v15, v72, v73 offset0:176 offset1:241
	v_add_u32_e32 v15, 0xdc00, v193
	ds_write2_b32 v15, v74, v75 offset0:50 offset1:115
	v_add_u32_e32 v15, 0xe000, v193
	ds_write2_b32 v15, v76, v77 offset0:184 offset1:249
	v_add_u32_e32 v15, 0xe400, v193
	ds_write2_b32 v15, v78, v79 offset0:58 offset1:123

.Lscan_zw1:
	ds_read2_b32 v[14:15], v11 offset1:1
	ds_read2_b32 v[12:13], v12 offset1:1
	ds_read2_b32 v[10:11], v64 offset1:1
	s_waitcnt lgkmcnt(4)
	v_pk_mul_f32 v[64:65], v[54:55], v[54:55]
	v_add_f32_e32 v58, v58, v63
	v_add_f32_e32 v58, v58, v64
	s_waitcnt lgkmcnt(3)
	v_pk_mul_f32 v[66:67], v[56:57], v[56:57]
	v_add_f32_e32 v58, v58, v65
	v_add_f32_e32 v58, v58, v66
	s_waitcnt lgkmcnt(2)
	v_pk_mul_f32 v[68:69], v[14:15], v[14:15]
	v_add_f32_e32 v58, v58, v67
	v_add_f32_e32 v58, v58, v68
	s_waitcnt lgkmcnt(1)
	v_pk_mul_f32 v[70:71], v[12:13], v[12:13]
	v_add_f32_e32 v58, v58, v69
	v_add_f32_e32 v58, v58, v70
	s_waitcnt lgkmcnt(0)
	v_pk_mul_f32 v[72:73], v[10:11], v[10:11]
	v_add_f32_e32 v58, v58, v71
	v_add_f32_e32 v58, v58, v72
	v_add_f32_e32 v58, v58, v73
	ds_bpermute_b32 v59, v188, v58
	s_waitcnt lgkmcnt(0)
	v_add_f32_e32 v58, v58, v59
	ds_bpermute_b32 v59, v189, v58
	s_and_saveexec_b64 s[10:11], s[4:5]
	s_cbranch_execz .Lscan_nostore
	s_waitcnt lgkmcnt(0)
	v_add_f32_e32 v80, v58, v59
	v_lshlrev_b32_e32 v76, 16, v8
	v_and_b32_e32 v77, 0xffff0000, v8
	v_lshlrev_b32_e32 v8, 16, v9
	v_and_b32_e32 v9, 0xffff0000, v9
	v_lshlrev_b32_e32 v78, 16, v2
	v_and_b32_e32 v79, 0xffff0000, v2
	v_fmamk_f32 v2, v80, 0x3c800000, v194
	v_mul_f32_e32 v84, 0xbfb8aa3b, v76
	v_mul_f32_e32 v85, 0xbfb8aa3b, v77
	v_mul_f32_e32 v86, 0xbfb8aa3b, v8
	v_mul_f32_e32 v87, 0xbfb8aa3b, v9
	v_mul_f32_e32 v90, 0x4b800000, v2
	v_exp_f32_e32 v84, v84
	v_exp_f32_e32 v85, v85
	v_cmp_gt_f32_e32 vcc, s18, v2
	v_exp_f32_e32 v86, v86
	v_exp_f32_e32 v87, v87
	v_cndmask_b32_e32 v2, v2, v90, vcc
	v_rsq_f32_e32 v2, v2
	v_lshlrev_b32_e32 v58, 16, v6
	v_and_b32_e32 v59, 0xffff0000, v6
	v_lshlrev_b32_e32 v6, 16, v7
	v_and_b32_e32 v7, 0xffff0000, v7
	v_mul_f32_e32 v80, 0xbfb8aa3b, v58
	v_mul_f32_e32 v81, 0xbfb8aa3b, v59
	v_mul_f32_e32 v82, 0xbfb8aa3b, v6
	v_mul_f32_e32 v83, 0xbfb8aa3b, v7
	v_add_f32_e32 v84, 1.0, v84
	v_add_f32_e32 v85, 1.0, v85
	v_exp_f32_e32 v80, v80
	v_exp_f32_e32 v81, v81
	v_exp_f32_e32 v82, v82
	v_exp_f32_e32 v83, v83
	v_add_f32_e32 v86, 1.0, v86
	v_add_f32_e32 v87, 1.0, v87
	v_rcp_f32_e32 v84, v84
	v_rcp_f32_e32 v85, v85
	v_mul_f32_e32 v88, 0xbfb8aa3b, v78
	v_mul_f32_e32 v89, 0xbfb8aa3b, v79
	v_rcp_f32_e32 v86, v86
	v_rcp_f32_e32 v87, v87
	v_mul_f32_e32 v90, 0x45800000, v2
	v_exp_f32_e32 v88, v88
	v_exp_f32_e32 v89, v89
	v_cndmask_b32_e32 v90, v2, v90, vcc
	v_pk_mul_f32 v[52:53], v[52:53], v[90:91] op_sel_hi:[1,0]
	v_add_f32_e32 v80, 1.0, v80
	v_add_f32_e32 v81, 1.0, v81
	v_add_f32_e32 v82, 1.0, v82
	v_add_f32_e32 v83, 1.0, v83
	v_pk_mul_f32 v[54:55], v[54:55], v[90:91] op_sel_hi:[1,0]
	v_pk_mul_f32 v[76:77], v[84:85], v[76:77]
	v_rcp_f32_e32 v80, v80
	v_rcp_f32_e32 v81, v81
	v_rcp_f32_e32 v82, v82
	v_rcp_f32_e32 v83, v83
	v_pk_mul_f32 v[8:9], v[86:87], v[8:9]
	v_add_f32_e32 v88, 1.0, v88
	v_add_f32_e32 v89, 1.0, v89
	v_rcp_f32_e32 v88, v88
	v_rcp_f32_e32 v89, v89
	v_pk_mul_f32 v[48:49], v[48:49], v[90:91] op_sel_hi:[1,0]
	v_pk_mul_f32 v[50:51], v[50:51], v[90:91] op_sel_hi:[1,0]
	v_pk_mul_f32 v[58:59], v[80:81], v[58:59]
	v_pk_mul_f32 v[6:7], v[82:83], v[6:7]
	v_pk_mul_f32 v[56:57], v[56:57], v[90:91] op_sel_hi:[1,0]
	v_pk_mul_f32 v[14:15], v[14:15], v[90:91] op_sel_hi:[1,0]
	v_pk_mul_f32 v[12:13], v[12:13], v[90:91] op_sel_hi:[1,0]
	v_pk_mul_f32 v[10:11], v[10:11], v[90:91] op_sel_hi:[1,0]
	v_pk_mul_f32 v[48:49], v[48:49], v[240:241]
	v_pk_mul_f32 v[52:53], v[52:53], v[244:245]
	v_pk_mul_f32 v[54:55], v[54:55], v[246:247]
	v_pk_mul_f32 v[52:53], v[76:77], v[52:53]
	v_pk_mul_f32 v[54:55], v[8:9], v[54:55]
	v_cvt_pk_bf16_f32 v8, v52, v53
	v_lshlrev_b32_e32 v52, 16, v3
	v_and_b32_e32 v53, 0xffff0000, v3
	v_mul_f32_e32 v2, 0xbfb8aa3b, v52
	v_cvt_pk_bf16_f32 v9, v54, v55
	v_exp_f32_e32 v54, v2
	v_mul_f32_e32 v2, 0xbfb8aa3b, v53
	v_pk_mul_f32 v[50:51], v[50:51], v[242:243]
	v_exp_f32_e32 v55, v2
	v_pk_mul_f32 v[48:49], v[58:59], v[48:49]
	v_pk_mul_f32 v[50:51], v[6:7], v[50:51]
	v_cvt_pk_bf16_f32 v6, v48, v49
	v_cvt_pk_bf16_f32 v7, v50, v51
	v_pk_mul_f32 v[48:49], v[56:57], v[252:253]
	v_pk_mul_f32 v[50:51], v[88:89], v[78:79]
	v_pk_mul_f32 v[14:15], v[14:15], v[254:255]
	v_pk_mul_f32 v[2:3], v[50:51], v[48:49]
	v_lshlrev_b32_e32 v50, 16, v4
	v_add_f32_e32 v48, 1.0, v54
	v_add_f32_e32 v49, 1.0, v55
	v_cvt_pk_bf16_f32 v2, v2, v3
	v_and_b32_e32 v51, 0xffff0000, v4
	v_mul_f32_e32 v3, 0xbfb8aa3b, v50
	v_rcp_f32_e32 v48, v48
	v_rcp_f32_e32 v49, v49
	v_exp_f32_e32 v3, v3
	v_mul_f32_e32 v4, 0xbfb8aa3b, v51
	v_exp_f32_e32 v4, v4
	v_pk_mul_f32 v[48:49], v[48:49], v[52:53]
	v_add_f32_e32 v3, 1.0, v3
	v_pk_mul_f32 v[14:15], v[48:49], v[14:15]
	v_rcp_f32_e32 v48, v3
	v_add_f32_e32 v3, 1.0, v4
	v_rcp_f32_e32 v49, v3
	v_cvt_pk_bf16_f32 v3, v14, v15
	v_pk_mul_f32 v[12:13], v[12:13], v[248:249]
	v_pk_mul_f32 v[10:11], v[10:11], v[250:251]
	v_pk_mul_f32 v[14:15], v[48:49], v[50:51]
	v_lshlrev_b32_e32 v48, 16, v5
	v_and_b32_e32 v49, 0xffff0000, v5
	v_mul_f32_e32 v4, 0xbfb8aa3b, v48
	v_exp_f32_e32 v50, v4
	v_mul_f32_e32 v4, 0xbfb8aa3b, v49
	v_exp_f32_e32 v51, v4
	v_pk_mul_f32 v[4:5], v[14:15], v[12:13]
	v_add_f32_e32 v12, 1.0, v50
	v_rcp_f32_e32 v12, v12
	v_add_f32_e32 v13, 1.0, v51
	v_rcp_f32_e32 v13, v13
	v_cvt_pk_bf16_f32 v4, v4, v5
	v_pk_mul_f32 v[12:13], v[12:13], v[48:49]
	s_nop 0
	v_pk_mul_f32 v[10:11], v[12:13], v[10:11]
	s_nop 0
	v_cvt_pk_bf16_f32 v5, v10, v11
	v_lshlrev_b64 v[10:11], 10, v[0:1]
	v_lshl_add_u64 v[10:11], v[160:161], 0, v[10:11]
	global_store_dwordx4 v[10:11], v[6:9], off
	global_store_dwordx4 v[10:11], v[2:5], off offset:16
	s_waitcnt vmcnt(2)
	s_branch .LBB0_3213

.Lscan_passive:
	s_barrier
	s_barrier
	s_movk_i32 s0, 0x41
.Lscan_ploop:
	s_barrier
	s_barrier
	s_sub_u32 s0, s0, 1
	s_cmp_lg_u32 s0, 0
	s_cbranch_scc1 .Lscan_ploop
	s_branch .Lattn_setup

	.amdhsa_kernel _Z6k_mega1P
		.amdhsa_group_segment_fixed_size 148560
		.amdhsa_private_segment_fixed_size 0
		.amdhsa_kernarg_size 464
		.amdhsa_user_sgpr_count 2
		.amdhsa_user_sgpr_dispatch_ptr 0
		.amdhsa_user_sgpr_queue_ptr 0
		.amdhsa_user_sgpr_kernarg_segment_ptr 1
		.amdhsa_user_sgpr_dispatch_id 0
		.amdhsa_user_sgpr_kernarg_preload_length 0
		.amdhsa_user_sgpr_kernarg_preload_offset 0
		.amdhsa_user_sgpr_private_segment_size 0
		.amdhsa_uses_dynamic_stack 0
		.amdhsa_enable_private_segment 0
		.amdhsa_system_sgpr_workgroup_id_x 1
		.amdhsa_system_sgpr_workgroup_id_y 0
		.amdhsa_system_sgpr_workgroup_id_z 0
		.amdhsa_system_sgpr_workgroup_info 0
		.amdhsa_system_vgpr_workitem_id 2
		.amdhsa_next_free_vgpr 256
		.amdhsa_next_free_sgpr 98
		.amdhsa_accum_offset 256
		.amdhsa_reserve_vcc 1
		.amdhsa_float_round_mode_32 0
		.amdhsa_float_round_mode_16_64 0
		.amdhsa_float_denorm_mode_32 3
		.amdhsa_float_denorm_mode_16_64 3
		.amdhsa_dx10_clamp 1
		.amdhsa_ieee_mode 1
		.amdhsa_fp16_overflow 0
		.amdhsa_tg_split 0
		.amdhsa_exception_fp_ieee_invalid_op 0
		.amdhsa_exception_fp_denorm_src 0
		.amdhsa_exception_fp_ieee_div_zero 0
		.amdhsa_exception_fp_ieee_overflow 0
		.amdhsa_exception_fp_ieee_underflow 0
		.amdhsa_exception_fp_ieee_inexact 0
		.amdhsa_exception_int_div_zero 0
	.end_amdhsa_kernel

amdhsa.kernels:
  - .agpr_count:     0
    .args:
      - .offset:         0
        .size:           208
        .value_kind:     by_value
      - .offset:         208
        .size:           4
        .value_kind:     hidden_block_count_x
      - .offset:         212
        .size:           4
        .value_kind:     hidden_block_count_y
      - .offset:         216
        .size:           4
        .value_kind:     hidden_block_count_z
      - .offset:         220
        .size:           2
        .value_kind:     hidden_group_size_x
      - .offset:         222
        .size:           2
        .value_kind:     hidden_group_size_y
      - .offset:         224
        .size:           2
        .value_kind:     hidden_group_size_z
      - .offset:         226
        .size:           2
        .value_kind:     hidden_remainder_x
      - .offset:         228
        .size:           2
        .value_kind:     hidden_remainder_y
      - .offset:         230
        .size:           2
        .value_kind:     hidden_remainder_z
      - .offset:         248
        .size:           8
        .value_kind:     hidden_global_offset_x
      - .offset:         256
        .size:           8
        .value_kind:     hidden_global_offset_y
      - .offset:         264
        .size:           8
        .value_kind:     hidden_global_offset_z
      - .offset:         272
        .size:           2
        .value_kind:     hidden_grid_dims
      - .offset:         296
        .size:           8
        .value_kind:     hidden_multigrid_sync_arg
    .group_segment_fixed_size: 148560
    .kernarg_segment_align: 8
    .kernarg_segment_size: 464
    .language:       OpenCL C
    .language_version:
      - 2
      - 0
    .max_flat_workgroup_size: 512
    .name:           _Z6k_mega1P
    .private_segment_fixed_size: 0
    .sgpr_count:     104
    .sgpr_spill_count: 30
    .symbol:         _Z6k_mega1P.kd
    .uniform_work_group_size: 1
    .uses_dynamic_stack: false
    .vgpr_count:     256
    .vgpr_spill_count: 0
    .wavefront_size: 64
